# stack10 plus write-through sc0 sc1 on the Q, K, P, U, V^T and gm_v^T stores of the G1 epilogues
# speedup vs baseline: 1.0166x; 1.0057x over previous
; __device__ __forceinline__ unsigned pk2(float lo, float hi) { f32v2 v = {lo, hi}; bf16v2 r = __builtin_convertvector(v, bf16v2); return __builtin_bit_cast(unsigned, r); }
; __device__ __forceinline__ float gelu_tanh_f(float x) { const float t = x * (1.0f + 0.044715f * x * x); return x * __builtin_amdgcn_rcpf(1.0f + __builtin_amdgcn_exp2f(-2.3022081981f * t)); }
;     __device__ __forceinline__ void operator()(f32x4 (&acc)[2][2][4][2], const Unit& u, int wr, int wc, int fr, int fq) const {
;     ...
;                     } else if constexpr (MODE == 3) {
;                         bf16_t* dst; const size_t tokc = (size_t)(u.pn * BM + cl);
;                         if (u.pm < 2) dst = O + ((tokc >> 5) * 512 + row) * 32 + (tokc & 31);
;                         else {
; #pragma unroll
;                             for (int e = 0; e < 4; ++e) { v0[e] = gelu_tanh_f(v0[e]); v1[e] = gelu_tanh_f(v1[e]); }
;                             dst = O2 + ((tokc >> 5) * 256 + (row - 512)) * 32 + (tokc & 31);
;                         }
;                         u32x4 w; w.x = pk2(v0[0], v0[1]); w.y = pk2(v0[2], v0[3]); w.z = pk2(v1[0], v1[1]); w.w = pk2(v1[2], v1[3]);
;                         *(u32x4*)dst = w;
.LBB0_245:
	s_lshl_b32 s27, s70, 8
	v_or_b32_e32 v154, s27, v138
	v_ashrrev_i32_e32 v155, 31, v154
	v_lshlrev_b64 v[156:157], s38, v[154:155]
	v_and_b32_e32 v157, s47, v157
	v_and_b32_e32 v156, s46, v156
	v_lshl_add_u64 v[152:153], v[156:157], 0, v[152:153]
	s_add_u32 s6, s80, s6
	s_addc_u32 s7, s81, s7
	v_lshlrev_b64 v[152:153], 6, v[152:153]
	v_bitop3_b32 v147, s27, 24, v138 bitop3:0xc8
	v_lshl_add_u64 v[152:153], s[6:7], 0, v[152:153]
	v_lshlrev_b32_e32 v178, 1, v147
	v_lshl_add_u64 v[152:153], v[152:153], 0, v[178:179]
	v_cvt_pk_bf16_f32 v128, v128, v129
	v_cvt_pk_bf16_f32 v129, v130, v131
	v_cvt_pk_bf16_f32 v130, v132, v133
	v_cvt_pk_bf16_f32 v131, v134, v135
	global_store_dwordx4 v[152:153], v[128:131], off sc0 sc1
	v_mov_b64_e32 v[134:135], v[114:115]
	s_andn2_b64 vcc, exec, s[36:37]
	v_cndmask_b32_e64 v128, 0, 1, s[36:37]
	v_cmp_ne_u32_e64 s[6:7], 1, v128
	v_mov_b64_e32 v[130:131], v[118:119]
	v_mov_b64_e32 v[128:129], v[116:117]
	v_mov_b64_e32 v[132:133], v[112:113]
	s_mov_b64 s[36:37], s[0:1]
	s_cbranch_vccnz .LBB0_247
	v_mul_f32_e32 v129, 0x3d372713, v112
	v_fma_f32 v129, v112, v129, 1.0
	v_mul_f32_e32 v130, 0x3d372713, v117
	v_mul_f32_e32 v129, v112, v129
	v_fma_f32 v130, v117, v130, 1.0
	v_mul_f32_e32 v129, 0xc0135761, v129
	v_mul_f32_e32 v130, v117, v130
	v_exp_f32_e32 v129, v129
	v_mul_f32_e32 v130, 0xc0135761, v130
	v_exp_f32_e32 v130, v130
	v_mul_f32_e32 v131, 0x3d372713, v118
	v_add_f32_e32 v129, 1.0, v129
	v_rcp_f32_e32 v132, v129
	v_add_f32_e32 v129, 1.0, v130
	v_mul_f32_e32 v130, 0x3d372713, v113
	v_mul_f32_e32 v133, 0x3d372713, v114
	v_fma_f32 v130, v113, v130, 1.0
	v_fma_f32 v131, v118, v131, 1.0
	v_fma_f32 v133, v114, v133, 1.0
	v_mul_f32_e32 v130, v113, v130
	v_mul_f32_e32 v131, v118, v131
	v_mul_f32_e32 v133, v114, v133
	v_mul_f32_e32 v130, 0xc0135761, v130
	v_mul_f32_e32 v131, 0xc0135761, v131
	v_mul_f32_e32 v133, 0xc0135761, v133
	v_exp_f32_e32 v130, v130
	v_exp_f32_e32 v131, v131
	v_exp_f32_e32 v133, v133
	v_mul_f32_e32 v128, 0x3d372713, v116
	v_add_f32_e32 v147, 1.0, v130
	v_add_f32_e32 v130, 1.0, v131
	v_add_f32_e32 v131, 1.0, v133
	v_mul_f32_e32 v133, 0x3d372713, v119
	v_mul_f32_e32 v134, 0x3d372713, v115
	v_fma_f32 v128, v116, v128, 1.0
	v_fma_f32 v133, v119, v133, 1.0
	v_fma_f32 v134, v115, v134, 1.0
	v_mul_f32_e32 v128, v116, v128
	v_mul_f32_e32 v133, v119, v133
	v_mul_f32_e32 v134, v115, v134
	v_mul_f32_e32 v128, 0xc0135761, v128
	v_mul_f32_e32 v133, 0xc0135761, v133
	v_mul_f32_e32 v134, 0xc0135761, v134
	v_exp_f32_e32 v128, v128
	v_exp_f32_e32 v133, v133
	v_exp_f32_e32 v135, v134
	v_rcp_f32_e32 v134, v131
	v_add_f32_e32 v128, 1.0, v128
	v_add_f32_e32 v131, 1.0, v133
	v_add_f32_e32 v133, 1.0, v135
	v_rcp_f32_e32 v128, v128
	v_rcp_f32_e32 v129, v129
	v_rcp_f32_e32 v130, v130
	v_rcp_f32_e32 v131, v131
	v_rcp_f32_e32 v135, v133
	v_rcp_f32_e32 v133, v147
	s_mov_b32 s73, s1
	v_pk_mul_f32 v[130:131], v[118:119], v[130:131]
	v_pk_mul_f32 v[128:129], v[116:117], v[128:129]
	v_pk_mul_f32 v[134:135], v[114:115], v[134:135]
	v_pk_mul_f32 v[132:133], v[112:113], v[132:133]
	s_mov_b64 s[30:31], 0x11500000
	s_mov_b64 s[34:35], 3
	s_mov_b64 s[36:37], s[72:73]
	v_mov_b64_e32 v[150:151], v[148:149]
.LBB0_247:
	v_or_b32_e32 v148, 0x80, v154
	v_ashrrev_i32_e32 v149, 31, v148
	v_lshlrev_b64 v[152:153], s34, v[148:149]
	v_and_b32_e32 v153, s37, v153
	v_and_b32_e32 v152, s36, v152
	v_lshl_add_u64 v[150:151], v[152:153], 0, v[150:151]
	s_add_u32 s30, s80, s30
	s_addc_u32 s31, s81, s31
	v_lshlrev_b64 v[150:151], 6, v[150:151]
	v_bitop3_b32 v147, v154, 24, v229 bitop3:0xc8
	v_lshl_add_u64 v[152:153], s[30:31], 0, v[150:151]
	v_lshlrev_b32_e32 v150, 1, v147
	v_mov_b32_e32 v151, v179
	v_lshl_add_u64 v[152:153], v[152:153], 0, v[150:151]
	v_cvt_pk_bf16_f32 v128, v128, v129
	v_cvt_pk_bf16_f32 v129, v130, v131
	v_cvt_pk_bf16_f32 v130, v132, v133
	v_cvt_pk_bf16_f32 v131, v134, v135
	v_or_b32_e32 v158, 16, v146
	global_store_dwordx4 v[152:153], v[128:131], off sc0 sc1
	v_ashrrev_i32_e32 v159, 31, v158
	v_lshl_add_u64 v[156:157], v[158:159], 0, s[0:1]
	v_lshlrev_b64 v[128:129], 3, v[154:155]
	s_mov_b64 s[30:31], -1
	s_and_b64 vcc, exec, s[6:7]
	v_and_b32_e32 v153, 0x3ffffff, v129
	v_and_b32_e32 v152, 0xfffffb00, v128
	s_cbranch_vccnz .LBB0_249
	v_mul_f32_e32 v129, 0x3d372713, v104
	v_fma_f32 v129, v104, v129, 1.0
	v_mul_f32_e32 v130, 0x3d372713, v109
	v_mul_f32_e32 v129, v104, v129
	v_fma_f32 v130, v109, v130, 1.0
	v_mul_f32_e32 v129, 0xc0135761, v129
	v_mul_f32_e32 v130, v109, v130
	v_exp_f32_e32 v129, v129
	v_mul_f32_e32 v130, 0xc0135761, v130
	v_exp_f32_e32 v130, v130
	v_mul_f32_e32 v131, 0x3d372713, v110
	v_add_f32_e32 v129, 1.0, v129
	v_rcp_f32_e32 v132, v129
	v_add_f32_e32 v129, 1.0, v130
	v_mul_f32_e32 v130, 0x3d372713, v105
	v_mul_f32_e32 v133, 0x3d372713, v106
	v_fma_f32 v130, v105, v130, 1.0
	v_fma_f32 v131, v110, v131, 1.0
	v_fma_f32 v133, v106, v133, 1.0
	v_mul_f32_e32 v130, v105, v130
	v_mul_f32_e32 v131, v110, v131
	v_mul_f32_e32 v133, v106, v133
	v_mul_f32_e32 v130, 0xc0135761, v130
	v_mul_f32_e32 v131, 0xc0135761, v131
	v_mul_f32_e32 v133, 0xc0135761, v133
	v_exp_f32_e32 v130, v130
	v_exp_f32_e32 v131, v131
	v_exp_f32_e32 v133, v133
	v_mul_f32_e32 v128, 0x3d372713, v108
	v_add_f32_e32 v147, 1.0, v130
	v_add_f32_e32 v130, 1.0, v131
	v_add_f32_e32 v131, 1.0, v133
	v_mul_f32_e32 v133, 0x3d372713, v111
	v_mul_f32_e32 v134, 0x3d372713, v107
	v_fma_f32 v128, v108, v128, 1.0
	v_fma_f32 v133, v111, v133, 1.0
	v_fma_f32 v134, v107, v134, 1.0
	v_mul_f32_e32 v128, v108, v128
	v_mul_f32_e32 v133, v111, v133
	v_mul_f32_e32 v134, v107, v134
	v_mul_f32_e32 v128, 0xc0135761, v128
	v_mul_f32_e32 v133, 0xc0135761, v133
	v_mul_f32_e32 v134, 0xc0135761, v134
	v_exp_f32_e32 v128, v128
	v_exp_f32_e32 v133, v133
	v_exp_f32_e32 v135, v134
	v_rcp_f32_e32 v134, v131
	v_add_f32_e32 v128, 1.0, v128
	v_add_f32_e32 v131, 1.0, v133
	v_add_f32_e32 v133, 1.0, v135
	v_rcp_f32_e32 v128, v128
	v_rcp_f32_e32 v129, v129
	v_rcp_f32_e32 v130, v130
	v_rcp_f32_e32 v131, v131
	v_rcp_f32_e32 v135, v133
	v_rcp_f32_e32 v133, v147
	v_pk_mul_f32 v[128:129], v[108:109], v[128:129]
	v_pk_mul_f32 v[130:131], v[110:111], v[130:131]
	v_pk_mul_f32 v[134:135], v[106:107], v[134:135]
	v_pk_mul_f32 v[132:133], v[104:105], v[132:133]
	v_lshl_add_u64 v[160:161], v[156:157], 0, v[152:153]
	s_mov_b64 s[30:31], 0

; __device__ __forceinline__ unsigned pk2(float lo, float hi) { f32v2 v = {lo, hi}; bf16v2 r = __builtin_convertvector(v, bf16v2); return __builtin_bit_cast(unsigned, r); }
; __device__ __forceinline__ float gelu_tanh_f(float x) { const float t = x * (1.0f + 0.044715f * x * x); return x * __builtin_amdgcn_rcpf(1.0f + __builtin_amdgcn_exp2f(-2.3022081981f * t)); }
;     __device__ __forceinline__ void operator()(f32x4 (&acc)[2][2][4][2], const Unit& u, int wr, int wc, int fr, int fq) const {
;     ...
;                     } else if constexpr (MODE == 3) {
;                         bf16_t* dst; const size_t tokc = (size_t)(u.pn * BM + cl);
;                         if (u.pm < 2) dst = O + ((tokc >> 5) * 512 + row) * 32 + (tokc & 31);
;                         else {
; #pragma unroll
;                             for (int e = 0; e < 4; ++e) { v0[e] = gelu_tanh_f(v0[e]); v1[e] = gelu_tanh_f(v1[e]); }
;                             dst = O2 + ((tokc >> 5) * 256 + (row - 512)) * 32 + (tokc & 31);
;                         }
;                         u32x4 w; w.x = pk2(v0[0], v0[1]); w.y = pk2(v0[2], v0[3]); w.z = pk2(v1[0], v1[1]); w.w = pk2(v1[2], v1[3]);
;                         *(u32x4*)dst = w;
.LBB0_251:
	s_add_u32 s30, s80, s34
	s_addc_u32 s31, s81, s35
	v_lshlrev_b64 v[160:161], 6, v[160:161]
	v_lshl_add_u64 v[160:161], s[30:31], 0, v[160:161]
	v_lshl_add_u64 v[160:161], v[160:161], 0, v[178:179]
	v_cvt_pk_bf16_f32 v128, v128, v129
	v_cvt_pk_bf16_f32 v129, v130, v131
	v_cvt_pk_bf16_f32 v130, v132, v133
	v_cvt_pk_bf16_f32 v131, v134, v135
	s_and_b64 vcc, exec, s[6:7]
	global_store_dwordx4 v[160:161], v[128:131], off sc0 sc1
	s_cbranch_vccnz .LBB0_255
	s_nop 0
	v_mul_f32_e32 v129, 0x3d372713, v96
	v_fma_f32 v129, v96, v129, 1.0
	v_mul_f32_e32 v130, 0x3d372713, v101
	v_mul_f32_e32 v129, v96, v129
	v_fma_f32 v130, v101, v130, 1.0
	v_mul_f32_e32 v129, 0xc0135761, v129
	v_mul_f32_e32 v130, v101, v130
	v_exp_f32_e32 v129, v129
	v_mul_f32_e32 v130, 0xc0135761, v130
	v_exp_f32_e32 v130, v130
	v_mul_f32_e32 v131, 0x3d372713, v102
	v_add_f32_e32 v129, 1.0, v129
	v_rcp_f32_e32 v132, v129
	v_add_f32_e32 v129, 1.0, v130
	v_mul_f32_e32 v130, 0x3d372713, v97
	v_mul_f32_e32 v133, 0x3d372713, v98
	v_fma_f32 v130, v97, v130, 1.0
	v_fma_f32 v131, v102, v131, 1.0
	v_fma_f32 v133, v98, v133, 1.0
	v_mul_f32_e32 v130, v97, v130
	v_mul_f32_e32 v131, v102, v131
	v_mul_f32_e32 v133, v98, v133
	v_mul_f32_e32 v130, 0xc0135761, v130
	v_mul_f32_e32 v131, 0xc0135761, v131
	v_mul_f32_e32 v133, 0xc0135761, v133
	v_exp_f32_e32 v130, v130
	v_exp_f32_e32 v131, v131
	v_exp_f32_e32 v133, v133
	v_mul_f32_e32 v128, 0x3d372713, v100
	v_add_f32_e32 v147, 1.0, v130
	v_add_f32_e32 v130, 1.0, v131
	v_add_f32_e32 v131, 1.0, v133
	v_mul_f32_e32 v133, 0x3d372713, v103
	v_mul_f32_e32 v134, 0x3d372713, v99
	v_fma_f32 v128, v100, v128, 1.0
	v_fma_f32 v133, v103, v133, 1.0
	v_fma_f32 v134, v99, v134, 1.0
	v_mul_f32_e32 v128, v100, v128
	v_mul_f32_e32 v133, v103, v133
	v_mul_f32_e32 v134, v99, v134
	v_mul_f32_e32 v128, 0xc0135761, v128
	v_mul_f32_e32 v133, 0xc0135761, v133
	v_mul_f32_e32 v134, 0xc0135761, v134
	v_exp_f32_e32 v128, v128
	v_exp_f32_e32 v133, v133
	v_exp_f32_e32 v135, v134
	v_rcp_f32_e32 v134, v131
	v_add_f32_e32 v128, 1.0, v128
	v_add_f32_e32 v131, 1.0, v133
	v_add_f32_e32 v133, 1.0, v135
	v_rcp_f32_e32 v128, v128
	v_rcp_f32_e32 v129, v129
	v_rcp_f32_e32 v130, v130
	v_rcp_f32_e32 v131, v131
	v_rcp_f32_e32 v135, v133
	v_rcp_f32_e32 v133, v147
	s_mov_b32 s73, s1
	v_pk_mul_f32 v[130:131], v[102:103], v[130:131]
	v_pk_mul_f32 v[128:129], v[100:101], v[128:129]
	v_pk_mul_f32 v[134:135], v[98:99], v[134:135]
	v_pk_mul_f32 v[132:133], v[96:97], v[132:133]
	s_mov_b64 s[30:31], 0x11500000
	s_mov_b64 s[34:35], 3
	s_mov_b64 s[36:37], s[72:73]
	s_branch .LBB0_256

; __device__ __forceinline__ unsigned pk2(float lo, float hi) { f32v2 v = {lo, hi}; bf16v2 r = __builtin_convertvector(v, bf16v2); return __builtin_bit_cast(unsigned, r); }
; __device__ __forceinline__ float sigmoid_f(float x) { return __builtin_amdgcn_rcpf(1.0f + __builtin_amdgcn_exp2f(-1.4426950409f * x)); }
; __device__ __forceinline__ float gelu_tanh_f(float x) { const float t = x * (1.0f + 0.044715f * x * x); return x * __builtin_amdgcn_rcpf(1.0f + __builtin_amdgcn_exp2f(-2.3022081981f * t)); }
;     __device__ __forceinline__ void operator()(f32x4 (&acc)[2][2][4][2], const Unit& u, int wr, int wc, int fr, int fq) const {
;     ...
;                     } else if constexpr (MODE == 2) {
;                         const int pn = u.pn;
;                         if (pn == 4) {
;                             u32x4 w; w.x = pk2(v0[0], v0[1]); w.y = pk2(v0[2], v0[3]); w.z = pk2(v1[0], v1[1]); w.w = pk2(v1[2], v1[3]);
;                             *(u32x4*)((bf16_t*)OF + row * 256 + cl) = w;
;                         } else {
;                             bf16_t* dst;
;                             if (pn < 2) { v0 = v0 * QSCALE; v1 = v1 * QSCALE; dst = O + row * 512 + pn * 256 + cl; }
;                             else if (pn < 4) { dst = O2 + row * 512 + (pn - 2) * 256 + cl; }
;                             else if (pn == 5) {
; #pragma unroll
;                                 for (int e = 0; e < 4; ++e) { v0[e] = gelu_tanh_f(v0[e]); v1[e] = gelu_tanh_f(v1[e]); }
;                                 dst = O3 + row * 256 + cl;
;                             } else {
; #pragma unroll
;                                 for (int e = 0; e < 4; ++e) { v0[e] = fmaxf(sigmoid_f(v0[e]), 1e-13f); v1[e] = fmaxf(sigmoid_f(v1[e]), 1e-13f); }
;                                 dst = O4 + row * 3072 + (pn - 6) * 256 + cl;
;                             }
;                             u32x4 w; w.x = pk2(v0[0], v0[1]); w.y = pk2(v0[2], v0[3]); w.z = pk2(v1[0], v1[1]); w.w = pk2(v1[2], v1[3]);
;                             if (pn >= 6) __builtin_nontemporal_store(w, (u32x4*)dst); else *(u32x4*)dst = w;
;                         }
.LBB0_314:
	v_lshlrev_b32_e32 v178, 1, v138
	v_lshl_add_u64 v[158:159], v[154:155], 0, v[178:179]
	v_cvt_pk_bf16_f32 v154, v148, v149
	v_cvt_pk_bf16_f32 v155, v152, v153
	v_cvt_pk_bf16_f32 v156, v134, v135
	v_cvt_pk_bf16_f32 v157, v150, v151
	s_mov_b64 s[6:7], 0
	global_store_dwordx4 v[158:159], v[154:157], off sc0 sc1
.LBB0_315:
	s_and_b64 vcc, exec, s[6:7]
	s_cbranch_vccz .LBB0_317
	v_cvt_pk_bf16_f32 v148, v124, v125
	v_cvt_pk_bf16_f32 v149, v126, v127
	v_cvt_pk_bf16_f32 v150, v120, v121
	v_cvt_pk_bf16_f32 v151, v122, v123
	v_lshl_add_u64 v[134:135], v[140:141], 0, v[128:129]
	global_store_dwordx4 v[134:135], v[148:151], off sc0 sc1

; __device__ __forceinline__ unsigned pk2(float lo, float hi) { f32v2 v = {lo, hi}; bf16v2 r = __builtin_convertvector(v, bf16v2); return __builtin_bit_cast(unsigned, r); }
; __device__ __forceinline__ float sigmoid_f(float x) { return __builtin_amdgcn_rcpf(1.0f + __builtin_amdgcn_exp2f(-1.4426950409f * x)); }
; __device__ __forceinline__ float gelu_tanh_f(float x) { const float t = x * (1.0f + 0.044715f * x * x); return x * __builtin_amdgcn_rcpf(1.0f + __builtin_amdgcn_exp2f(-2.3022081981f * t)); }
;     __device__ __forceinline__ void operator()(f32x4 (&acc)[2][2][4][2], const Unit& u, int wr, int wc, int fr, int fq) const {
;     ...
;                     } else if constexpr (MODE == 2) {
;                         const int pn = u.pn;
;                         if (pn == 4) {
;                             u32x4 w; w.x = pk2(v0[0], v0[1]); w.y = pk2(v0[2], v0[3]); w.z = pk2(v1[0], v1[1]); w.w = pk2(v1[2], v1[3]);
;                             *(u32x4*)((bf16_t*)OF + row * 256 + cl) = w;
;                         } else {
;                             bf16_t* dst;
;                             if (pn < 2) { v0 = v0 * QSCALE; v1 = v1 * QSCALE; dst = O + row * 512 + pn * 256 + cl; }
;                             else if (pn < 4) { dst = O2 + row * 512 + (pn - 2) * 256 + cl; }
;                             else if (pn == 5) {
; #pragma unroll
;                                 for (int e = 0; e < 4; ++e) { v0[e] = gelu_tanh_f(v0[e]); v1[e] = gelu_tanh_f(v1[e]); }
;                                 dst = O3 + row * 256 + cl;
;                             } else {
; #pragma unroll
;                                 for (int e = 0; e < 4; ++e) { v0[e] = fmaxf(sigmoid_f(v0[e]), 1e-13f); v1[e] = fmaxf(sigmoid_f(v1[e]), 1e-13f); }
;                                 dst = O4 + row * 3072 + (pn - 6) * 256 + cl;
;                             }
;                             u32x4 w; w.x = pk2(v0[0], v0[1]); w.y = pk2(v0[2], v0[3]); w.z = pk2(v1[0], v1[1]); w.w = pk2(v1[2], v1[3]);
;                             if (pn >= 6) __builtin_nontemporal_store(w, (u32x4*)dst); else *(u32x4*)dst = w;
;                         }
.LBB0_330:
	v_lshlrev_b32_e32 v178, 1, v138
	v_lshl_add_u64 v[154:155], v[154:155], 0, v[178:179]
	v_cvt_pk_bf16_f32 v130, v148, v149
	v_cvt_pk_bf16_f32 v131, v152, v153
	v_cvt_pk_bf16_f32 v132, v134, v135
	v_cvt_pk_bf16_f32 v133, v150, v151
	s_mov_b64 s[30:31], 0
	global_store_dwordx4 v[154:155], v[130:133], off offset:256 sc0 sc1
.LBB0_331:
	s_and_b64 vcc, exec, s[30:31]
	s_cbranch_vccz .LBB0_333
	v_cvt_pk_bf16_f32 v130, v116, v117
	v_cvt_pk_bf16_f32 v131, v118, v119
	v_cvt_pk_bf16_f32 v132, v112, v113
	v_cvt_pk_bf16_f32 v133, v114, v115
	v_lshl_add_u64 v[128:129], v[142:143], 0, v[128:129]
	global_store_dwordx4 v[128:129], v[130:133], off sc0 sc1

; __device__ __forceinline__ unsigned pk2(float lo, float hi) { f32v2 v = {lo, hi}; bf16v2 r = __builtin_convertvector(v, bf16v2); return __builtin_bit_cast(unsigned, r); }
; __device__ __forceinline__ float sigmoid_f(float x) { return __builtin_amdgcn_rcpf(1.0f + __builtin_amdgcn_exp2f(-1.4426950409f * x)); }
; __device__ __forceinline__ float gelu_tanh_f(float x) { const float t = x * (1.0f + 0.044715f * x * x); return x * __builtin_amdgcn_rcpf(1.0f + __builtin_amdgcn_exp2f(-2.3022081981f * t)); }
;     __device__ __forceinline__ void operator()(f32x4 (&acc)[2][2][4][2], const Unit& u, int wr, int wc, int fr, int fq) const {
;     ...
;                     } else if constexpr (MODE == 2) {
;                         const int pn = u.pn;
;                         if (pn == 4) {
;                             u32x4 w; w.x = pk2(v0[0], v0[1]); w.y = pk2(v0[2], v0[3]); w.z = pk2(v1[0], v1[1]); w.w = pk2(v1[2], v1[3]);
;                             *(u32x4*)((bf16_t*)OF + row * 256 + cl) = w;
;                         } else {
;                             bf16_t* dst;
;                             if (pn < 2) { v0 = v0 * QSCALE; v1 = v1 * QSCALE; dst = O + row * 512 + pn * 256 + cl; }
;                             else if (pn < 4) { dst = O2 + row * 512 + (pn - 2) * 256 + cl; }
;                             else if (pn == 5) {
; #pragma unroll
;                                 for (int e = 0; e < 4; ++e) { v0[e] = gelu_tanh_f(v0[e]); v1[e] = gelu_tanh_f(v1[e]); }
;                                 dst = O3 + row * 256 + cl;
;                             } else {
; #pragma unroll
;                                 for (int e = 0; e < 4; ++e) { v0[e] = fmaxf(sigmoid_f(v0[e]), 1e-13f); v1[e] = fmaxf(sigmoid_f(v1[e]), 1e-13f); }
;                                 dst = O4 + row * 3072 + (pn - 6) * 256 + cl;
;                             }
;                             u32x4 w; w.x = pk2(v0[0], v0[1]); w.y = pk2(v0[2], v0[3]); w.z = pk2(v1[0], v1[1]); w.w = pk2(v1[2], v1[3]);
;                             if (pn >= 6) __builtin_nontemporal_store(w, (u32x4*)dst); else *(u32x4*)dst = w;
;                         }
.LBB0_346:
	v_lshlrev_b32_e32 v178, 1, v138
	v_lshl_add_u64 v[158:159], v[154:155], 0, v[178:179]
	v_cvt_pk_bf16_f32 v154, v148, v149
	v_cvt_pk_bf16_f32 v155, v152, v153
	v_cvt_pk_bf16_f32 v156, v134, v135
	v_cvt_pk_bf16_f32 v157, v150, v151
	global_store_dwordx4 v[158:159], v[154:157], off sc0 sc1

; __device__ __forceinline__ unsigned pk2(float lo, float hi) { f32v2 v = {lo, hi}; bf16v2 r = __builtin_convertvector(v, bf16v2); return __builtin_bit_cast(unsigned, r); }
; __device__ __forceinline__ float sigmoid_f(float x) { return __builtin_amdgcn_rcpf(1.0f + __builtin_amdgcn_exp2f(-1.4426950409f * x)); }
; __device__ __forceinline__ float gelu_tanh_f(float x) { const float t = x * (1.0f + 0.044715f * x * x); return x * __builtin_amdgcn_rcpf(1.0f + __builtin_amdgcn_exp2f(-2.3022081981f * t)); }
;     __device__ __forceinline__ void operator()(f32x4 (&acc)[2][2][4][2], const Unit& u, int wr, int wc, int fr, int fq) const {
;     ...
;                     } else if constexpr (MODE == 2) {
;                         const int pn = u.pn;
;                         if (pn == 4) {
;                             u32x4 w; w.x = pk2(v0[0], v0[1]); w.y = pk2(v0[2], v0[3]); w.z = pk2(v1[0], v1[1]); w.w = pk2(v1[2], v1[3]);
;                             *(u32x4*)((bf16_t*)OF + row * 256 + cl) = w;
;                         } else {
;                             bf16_t* dst;
;                             if (pn < 2) { v0 = v0 * QSCALE; v1 = v1 * QSCALE; dst = O + row * 512 + pn * 256 + cl; }
;                             else if (pn < 4) { dst = O2 + row * 512 + (pn - 2) * 256 + cl; }
;                             else if (pn == 5) {
; #pragma unroll
;                                 for (int e = 0; e < 4; ++e) { v0[e] = gelu_tanh_f(v0[e]); v1[e] = gelu_tanh_f(v1[e]); }
;                                 dst = O3 + row * 256 + cl;
;                             } else {
; #pragma unroll
;                                 for (int e = 0; e < 4; ++e) { v0[e] = fmaxf(sigmoid_f(v0[e]), 1e-13f); v1[e] = fmaxf(sigmoid_f(v1[e]), 1e-13f); }
;                                 dst = O4 + row * 3072 + (pn - 6) * 256 + cl;
;                             }
;                             u32x4 w; w.x = pk2(v0[0], v0[1]); w.y = pk2(v0[2], v0[3]); w.z = pk2(v1[0], v1[1]); w.w = pk2(v1[2], v1[3]);
;                             if (pn >= 6) __builtin_nontemporal_store(w, (u32x4*)dst); else *(u32x4*)dst = w;
;                         }
.LBB0_360:
	v_lshlrev_b32_e32 v178, 1, v138
	v_lshl_add_u64 v[154:155], v[154:155], 0, v[178:179]
	v_cvt_pk_bf16_f32 v130, v148, v149
	v_cvt_pk_bf16_f32 v131, v152, v153
	v_cvt_pk_bf16_f32 v132, v134, v135
	v_cvt_pk_bf16_f32 v133, v150, v151
	global_store_dwordx4 v[154:155], v[130:133], off offset:256 sc0 sc1
	s_branch .LBB0_365
.LBB0_361:
	s_and_b64 vcc, exec, s[30:31]
	s_cbranch_vccz .LBB0_347
	v_cvt_pk_bf16_f32 v148, v108, v109
	v_cvt_pk_bf16_f32 v149, v110, v111
	v_cvt_pk_bf16_f32 v150, v104, v105
	v_cvt_pk_bf16_f32 v151, v106, v107
	v_lshl_add_u64 v[134:135], v[140:141], 0, v[128:129]
	global_store_dwordx4 v[134:135], v[148:151], off sc0 sc1
	s_and_b64 vcc, exec, s[6:7]
	s_mov_b64 s[30:31], -1
	s_cbranch_vccz .LBB0_348
.LBB0_363:
	s_and_b64 vcc, exec, s[30:31]
	s_cbranch_vccz .LBB0_365
	v_cvt_pk_bf16_f32 v130, v100, v101
	v_cvt_pk_bf16_f32 v131, v102, v103
	v_cvt_pk_bf16_f32 v132, v96, v97
	v_cvt_pk_bf16_f32 v133, v98, v99
	v_lshl_add_u64 v[128:129], v[142:143], 0, v[128:129]
	global_store_dwordx4 v[128:129], v[130:133], off sc0 sc1

; __device__ __forceinline__ unsigned pk2(float lo, float hi) { f32v2 v = {lo, hi}; bf16v2 r = __builtin_convertvector(v, bf16v2); return __builtin_bit_cast(unsigned, r); }
; __device__ __forceinline__ float sigmoid_f(float x) { return __builtin_amdgcn_rcpf(1.0f + __builtin_amdgcn_exp2f(-1.4426950409f * x)); }
; __device__ __forceinline__ float gelu_tanh_f(float x) { const float t = x * (1.0f + 0.044715f * x * x); return x * __builtin_amdgcn_rcpf(1.0f + __builtin_amdgcn_exp2f(-2.3022081981f * t)); }
;     __device__ __forceinline__ void operator()(f32x4 (&acc)[2][2][4][2], const Unit& u, int wr, int wc, int fr, int fq) const {
;     ...
;                     } else if constexpr (MODE == 2) {
;                         const int pn = u.pn;
;                         if (pn == 4) {
;                             u32x4 w; w.x = pk2(v0[0], v0[1]); w.y = pk2(v0[2], v0[3]); w.z = pk2(v1[0], v1[1]); w.w = pk2(v1[2], v1[3]);
;                             *(u32x4*)((bf16_t*)OF + row * 256 + cl) = w;
;                         } else {
;                             bf16_t* dst;
;                             if (pn < 2) { v0 = v0 * QSCALE; v1 = v1 * QSCALE; dst = O + row * 512 + pn * 256 + cl; }
;                             else if (pn < 4) { dst = O2 + row * 512 + (pn - 2) * 256 + cl; }
;                             else if (pn == 5) {
; #pragma unroll
;                                 for (int e = 0; e < 4; ++e) { v0[e] = gelu_tanh_f(v0[e]); v1[e] = gelu_tanh_f(v1[e]); }
;                                 dst = O3 + row * 256 + cl;
;                             } else {
; #pragma unroll
;                                 for (int e = 0; e < 4; ++e) { v0[e] = fmaxf(sigmoid_f(v0[e]), 1e-13f); v1[e] = fmaxf(sigmoid_f(v1[e]), 1e-13f); }
;                                 dst = O4 + row * 3072 + (pn - 6) * 256 + cl;
;                             }
;                             u32x4 w; w.x = pk2(v0[0], v0[1]); w.y = pk2(v0[2], v0[3]); w.z = pk2(v1[0], v1[1]); w.w = pk2(v1[2], v1[3]);
;                             if (pn >= 6) __builtin_nontemporal_store(w, (u32x4*)dst); else *(u32x4*)dst = w;
;                         }
.LBB0_393:
	s_and_b64 vcc, exec, s[30:31]
	s_cbranch_vccz .LBB0_379
	v_cvt_pk_bf16_f32 v148, v92, v93
	v_cvt_pk_bf16_f32 v149, v94, v95
	v_cvt_pk_bf16_f32 v150, v88, v89
	v_cvt_pk_bf16_f32 v151, v90, v91
	v_lshl_add_u64 v[134:135], v[140:141], 0, v[128:129]
	global_store_dwordx4 v[134:135], v[148:151], off sc0 sc1
	s_and_b64 vcc, exec, s[6:7]
	s_mov_b64 s[30:31], -1
	s_cbranch_vccz .LBB0_380
.LBB0_395:
	s_and_b64 vcc, exec, s[30:31]
	s_cbranch_vccz .LBB0_397
	v_cvt_pk_bf16_f32 v130, v84, v85
	v_cvt_pk_bf16_f32 v131, v86, v87
	v_cvt_pk_bf16_f32 v132, v80, v81
	v_cvt_pk_bf16_f32 v133, v82, v83
	v_lshl_add_u64 v[128:129], v[142:143], 0, v[128:129]
	global_store_dwordx4 v[128:129], v[130:133], off sc0 sc1

; __device__ __forceinline__ unsigned pk2(float lo, float hi) { f32v2 v = {lo, hi}; bf16v2 r = __builtin_convertvector(v, bf16v2); return __builtin_bit_cast(unsigned, r); }
; __device__ __forceinline__ float sigmoid_f(float x) { return __builtin_amdgcn_rcpf(1.0f + __builtin_amdgcn_exp2f(-1.4426950409f * x)); }
; __device__ __forceinline__ float gelu_tanh_f(float x) { const float t = x * (1.0f + 0.044715f * x * x); return x * __builtin_amdgcn_rcpf(1.0f + __builtin_amdgcn_exp2f(-2.3022081981f * t)); }
;     __device__ __forceinline__ void operator()(f32x4 (&acc)[2][2][4][2], const Unit& u, int wr, int wc, int fr, int fq) const {
;     ...
;                     } else if constexpr (MODE == 2) {
;                         const int pn = u.pn;
;                         if (pn == 4) {
;                             u32x4 w; w.x = pk2(v0[0], v0[1]); w.y = pk2(v0[2], v0[3]); w.z = pk2(v1[0], v1[1]); w.w = pk2(v1[2], v1[3]);
;                             *(u32x4*)((bf16_t*)OF + row * 256 + cl) = w;
;                         } else {
;                             bf16_t* dst;
;                             if (pn < 2) { v0 = v0 * QSCALE; v1 = v1 * QSCALE; dst = O + row * 512 + pn * 256 + cl; }
;                             else if (pn < 4) { dst = O2 + row * 512 + (pn - 2) * 256 + cl; }
;                             else if (pn == 5) {
; #pragma unroll
;                                 for (int e = 0; e < 4; ++e) { v0[e] = gelu_tanh_f(v0[e]); v1[e] = gelu_tanh_f(v1[e]); }
;                                 dst = O3 + row * 256 + cl;
;                             } else {
; #pragma unroll
;                                 for (int e = 0; e < 4; ++e) { v0[e] = fmaxf(sigmoid_f(v0[e]), 1e-13f); v1[e] = fmaxf(sigmoid_f(v1[e]), 1e-13f); }
;                                 dst = O4 + row * 3072 + (pn - 6) * 256 + cl;
;                             }
;                             u32x4 w; w.x = pk2(v0[0], v0[1]); w.y = pk2(v0[2], v0[3]); w.z = pk2(v1[0], v1[1]); w.w = pk2(v1[2], v1[3]);
;                             if (pn >= 6) __builtin_nontemporal_store(w, (u32x4*)dst); else *(u32x4*)dst = w;
;                         }
.LBB0_425:
	s_and_b64 vcc, exec, s[30:31]
	s_cbranch_vccz .LBB0_411
	v_cvt_pk_bf16_f32 v148, v76, v77
	v_cvt_pk_bf16_f32 v149, v78, v79
	v_cvt_pk_bf16_f32 v150, v72, v73
	v_cvt_pk_bf16_f32 v151, v74, v75
	v_lshl_add_u64 v[134:135], v[140:141], 0, v[128:129]
	global_store_dwordx4 v[134:135], v[148:151], off sc0 sc1
	s_and_b64 vcc, exec, s[6:7]
	s_mov_b64 s[30:31], -1
	s_cbranch_vccz .LBB0_412
.LBB0_427:
	s_and_b64 vcc, exec, s[30:31]
	s_cbranch_vccz .LBB0_429
	v_cvt_pk_bf16_f32 v130, v68, v69
	v_cvt_pk_bf16_f32 v131, v70, v71
	v_cvt_pk_bf16_f32 v132, v64, v65
	v_cvt_pk_bf16_f32 v133, v66, v67
	v_lshl_add_u64 v[128:129], v[142:143], 0, v[128:129]
	global_store_dwordx4 v[128:129], v[130:133], off sc0 sc1

; __device__ __forceinline__ unsigned pk2(float lo, float hi) { f32v2 v = {lo, hi}; bf16v2 r = __builtin_convertvector(v, bf16v2); return __builtin_bit_cast(unsigned, r); }
; __device__ __forceinline__ float sigmoid_f(float x) { return __builtin_amdgcn_rcpf(1.0f + __builtin_amdgcn_exp2f(-1.4426950409f * x)); }
; __device__ __forceinline__ float gelu_tanh_f(float x) { const float t = x * (1.0f + 0.044715f * x * x); return x * __builtin_amdgcn_rcpf(1.0f + __builtin_amdgcn_exp2f(-2.3022081981f * t)); }
;     __device__ __forceinline__ void operator()(f32x4 (&acc)[2][2][4][2], const Unit& u, int wr, int wc, int fr, int fq) const {
;     ...
;                     } else if constexpr (MODE == 2) {
;                         const int pn = u.pn;
;                         if (pn == 4) {
;                             u32x4 w; w.x = pk2(v0[0], v0[1]); w.y = pk2(v0[2], v0[3]); w.z = pk2(v1[0], v1[1]); w.w = pk2(v1[2], v1[3]);
;                             *(u32x4*)((bf16_t*)OF + row * 256 + cl) = w;
;                         } else {
;                             bf16_t* dst;
;                             if (pn < 2) { v0 = v0 * QSCALE; v1 = v1 * QSCALE; dst = O + row * 512 + pn * 256 + cl; }
;                             else if (pn < 4) { dst = O2 + row * 512 + (pn - 2) * 256 + cl; }
;                             else if (pn == 5) {
; #pragma unroll
;                                 for (int e = 0; e < 4; ++e) { v0[e] = gelu_tanh_f(v0[e]); v1[e] = gelu_tanh_f(v1[e]); }
;                                 dst = O3 + row * 256 + cl;
;                             } else {
; #pragma unroll
;                                 for (int e = 0; e < 4; ++e) { v0[e] = fmaxf(sigmoid_f(v0[e]), 1e-13f); v1[e] = fmaxf(sigmoid_f(v1[e]), 1e-13f); }
;                                 dst = O4 + row * 3072 + (pn - 6) * 256 + cl;
;                             }
;                             u32x4 w; w.x = pk2(v0[0], v0[1]); w.y = pk2(v0[2], v0[3]); w.z = pk2(v1[0], v1[1]); w.w = pk2(v1[2], v1[3]);
;                             if (pn >= 6) __builtin_nontemporal_store(w, (u32x4*)dst); else *(u32x4*)dst = w;
;                         }
.LBB0_457:
	s_and_b64 vcc, exec, s[30:31]
	s_cbranch_vccz .LBB0_443
	v_cvt_pk_bf16_f32 v148, v60, v61
	v_cvt_pk_bf16_f32 v149, v62, v63
	v_cvt_pk_bf16_f32 v150, v56, v57
	v_cvt_pk_bf16_f32 v151, v58, v59
	v_lshl_add_u64 v[134:135], v[140:141], 0, v[128:129]
	global_store_dwordx4 v[134:135], v[148:151], off sc0 sc1
	s_and_b64 vcc, exec, s[6:7]
	s_mov_b64 s[30:31], -1
	s_cbranch_vccz .LBB0_444
.LBB0_459:
	s_and_b64 vcc, exec, s[30:31]
	s_cbranch_vccz .LBB0_461
	v_cvt_pk_bf16_f32 v130, v52, v53
	v_cvt_pk_bf16_f32 v131, v54, v55
	v_cvt_pk_bf16_f32 v132, v48, v49
	v_cvt_pk_bf16_f32 v133, v50, v51
	v_lshl_add_u64 v[128:129], v[142:143], 0, v[128:129]
	global_store_dwordx4 v[128:129], v[130:133], off sc0 sc1

; __device__ __forceinline__ unsigned pk2(float lo, float hi) { f32v2 v = {lo, hi}; bf16v2 r = __builtin_convertvector(v, bf16v2); return __builtin_bit_cast(unsigned, r); }
; __device__ __forceinline__ float sigmoid_f(float x) { return __builtin_amdgcn_rcpf(1.0f + __builtin_amdgcn_exp2f(-1.4426950409f * x)); }
; __device__ __forceinline__ float gelu_tanh_f(float x) { const float t = x * (1.0f + 0.044715f * x * x); return x * __builtin_amdgcn_rcpf(1.0f + __builtin_amdgcn_exp2f(-2.3022081981f * t)); }
;     __device__ __forceinline__ void operator()(f32x4 (&acc)[2][2][4][2], const Unit& u, int wr, int wc, int fr, int fq) const {
;     ...
;                     } else if constexpr (MODE == 2) {
;                         const int pn = u.pn;
;                         if (pn == 4) {
;                             u32x4 w; w.x = pk2(v0[0], v0[1]); w.y = pk2(v0[2], v0[3]); w.z = pk2(v1[0], v1[1]); w.w = pk2(v1[2], v1[3]);
;                             *(u32x4*)((bf16_t*)OF + row * 256 + cl) = w;
;                         } else {
;                             bf16_t* dst;
;                             if (pn < 2) { v0 = v0 * QSCALE; v1 = v1 * QSCALE; dst = O + row * 512 + pn * 256 + cl; }
;                             else if (pn < 4) { dst = O2 + row * 512 + (pn - 2) * 256 + cl; }
;                             else if (pn == 5) {
; #pragma unroll
;                                 for (int e = 0; e < 4; ++e) { v0[e] = gelu_tanh_f(v0[e]); v1[e] = gelu_tanh_f(v1[e]); }
;                                 dst = O3 + row * 256 + cl;
;                             } else {
; #pragma unroll
;                                 for (int e = 0; e < 4; ++e) { v0[e] = fmaxf(sigmoid_f(v0[e]), 1e-13f); v1[e] = fmaxf(sigmoid_f(v1[e]), 1e-13f); }
;                                 dst = O4 + row * 3072 + (pn - 6) * 256 + cl;
;                             }
;                             u32x4 w; w.x = pk2(v0[0], v0[1]); w.y = pk2(v0[2], v0[3]); w.z = pk2(v1[0], v1[1]); w.w = pk2(v1[2], v1[3]);
;                             if (pn >= 6) __builtin_nontemporal_store(w, (u32x4*)dst); else *(u32x4*)dst = w;
;                         }
.LBB0_489:
	s_and_b64 vcc, exec, s[30:31]
	s_cbranch_vccz .LBB0_475
	v_cvt_pk_bf16_f32 v148, v44, v45
	v_cvt_pk_bf16_f32 v149, v46, v47
	v_cvt_pk_bf16_f32 v150, v40, v41
	v_cvt_pk_bf16_f32 v151, v42, v43
	v_lshl_add_u64 v[134:135], v[140:141], 0, v[128:129]
	global_store_dwordx4 v[134:135], v[148:151], off sc0 sc1
	s_and_b64 vcc, exec, s[6:7]
	s_mov_b64 s[30:31], -1
	s_cbranch_vccz .LBB0_476
.LBB0_491:
	s_and_b64 vcc, exec, s[30:31]
	s_cbranch_vccz .LBB0_493
	v_cvt_pk_bf16_f32 v130, v36, v37
	v_cvt_pk_bf16_f32 v131, v38, v39
	v_cvt_pk_bf16_f32 v132, v32, v33
	v_cvt_pk_bf16_f32 v133, v34, v35
	v_lshl_add_u64 v[128:129], v[142:143], 0, v[128:129]
	global_store_dwordx4 v[128:129], v[130:133], off sc0 sc1

; __device__ __forceinline__ unsigned pk2(float lo, float hi) { f32v2 v = {lo, hi}; bf16v2 r = __builtin_convertvector(v, bf16v2); return __builtin_bit_cast(unsigned, r); }
; __device__ __forceinline__ float sigmoid_f(float x) { return __builtin_amdgcn_rcpf(1.0f + __builtin_amdgcn_exp2f(-1.4426950409f * x)); }
; __device__ __forceinline__ float gelu_tanh_f(float x) { const float t = x * (1.0f + 0.044715f * x * x); return x * __builtin_amdgcn_rcpf(1.0f + __builtin_amdgcn_exp2f(-2.3022081981f * t)); }
;     __device__ __forceinline__ void operator()(f32x4 (&acc)[2][2][4][2], const Unit& u, int wr, int wc, int fr, int fq) const {
;     ...
;                     } else if constexpr (MODE == 2) {
;                         const int pn = u.pn;
;                         if (pn == 4) {
;                             u32x4 w; w.x = pk2(v0[0], v0[1]); w.y = pk2(v0[2], v0[3]); w.z = pk2(v1[0], v1[1]); w.w = pk2(v1[2], v1[3]);
;                             *(u32x4*)((bf16_t*)OF + row * 256 + cl) = w;
;                         } else {
;                             bf16_t* dst;
;                             if (pn < 2) { v0 = v0 * QSCALE; v1 = v1 * QSCALE; dst = O + row * 512 + pn * 256 + cl; }
;                             else if (pn < 4) { dst = O2 + row * 512 + (pn - 2) * 256 + cl; }
;                             else if (pn == 5) {
; #pragma unroll
;                                 for (int e = 0; e < 4; ++e) { v0[e] = gelu_tanh_f(v0[e]); v1[e] = gelu_tanh_f(v1[e]); }
;                                 dst = O3 + row * 256 + cl;
;                             } else {
; #pragma unroll
;                                 for (int e = 0; e < 4; ++e) { v0[e] = fmaxf(sigmoid_f(v0[e]), 1e-13f); v1[e] = fmaxf(sigmoid_f(v1[e]), 1e-13f); }
;                                 dst = O4 + row * 3072 + (pn - 6) * 256 + cl;
;                             }
;                             u32x4 w; w.x = pk2(v0[0], v0[1]); w.y = pk2(v0[2], v0[3]); w.z = pk2(v1[0], v1[1]); w.w = pk2(v1[2], v1[3]);
;                             if (pn >= 6) __builtin_nontemporal_store(w, (u32x4*)dst); else *(u32x4*)dst = w;
;                         }
.LBB0_521:
	s_and_b64 vcc, exec, s[30:31]
	s_cbranch_vccz .LBB0_507
	v_cvt_pk_bf16_f32 v148, v28, v29
	v_cvt_pk_bf16_f32 v149, v30, v31
	v_cvt_pk_bf16_f32 v150, v24, v25
	v_cvt_pk_bf16_f32 v151, v26, v27
	v_lshl_add_u64 v[134:135], v[140:141], 0, v[128:129]
	global_store_dwordx4 v[134:135], v[148:151], off sc0 sc1
	s_and_b64 vcc, exec, s[6:7]
	s_mov_b64 s[30:31], -1
	s_cbranch_vccz .LBB0_508
.LBB0_523:
	s_and_b64 vcc, exec, s[30:31]
	s_cbranch_vccz .LBB0_525
	v_cvt_pk_bf16_f32 v130, v20, v21
	v_cvt_pk_bf16_f32 v131, v22, v23
	v_cvt_pk_bf16_f32 v132, v16, v17
	v_cvt_pk_bf16_f32 v133, v18, v19
	v_lshl_add_u64 v[128:129], v[142:143], 0, v[128:129]
	global_store_dwordx4 v[128:129], v[130:133], off sc0 sc1

; __device__ __forceinline__ unsigned pk2(float lo, float hi) { f32v2 v = {lo, hi}; bf16v2 r = __builtin_convertvector(v, bf16v2); return __builtin_bit_cast(unsigned, r); }
; __device__ __forceinline__ float sigmoid_f(float x) { return __builtin_amdgcn_rcpf(1.0f + __builtin_amdgcn_exp2f(-1.4426950409f * x)); }
; __device__ __forceinline__ float gelu_tanh_f(float x) { const float t = x * (1.0f + 0.044715f * x * x); return x * __builtin_amdgcn_rcpf(1.0f + __builtin_amdgcn_exp2f(-2.3022081981f * t)); }
;     __device__ __forceinline__ void operator()(f32x4 (&acc)[2][2][4][2], const Unit& u, int wr, int wc, int fr, int fq) const {
;     ...
;                     } else if constexpr (MODE == 2) {
;                         const int pn = u.pn;
;                         if (pn == 4) {
;                             u32x4 w; w.x = pk2(v0[0], v0[1]); w.y = pk2(v0[2], v0[3]); w.z = pk2(v1[0], v1[1]); w.w = pk2(v1[2], v1[3]);
;                             *(u32x4*)((bf16_t*)OF + row * 256 + cl) = w;
;                         } else {
;                             bf16_t* dst;
;                             if (pn < 2) { v0 = v0 * QSCALE; v1 = v1 * QSCALE; dst = O + row * 512 + pn * 256 + cl; }
;                             else if (pn < 4) { dst = O2 + row * 512 + (pn - 2) * 256 + cl; }
;                             else if (pn == 5) {
; #pragma unroll
;                                 for (int e = 0; e < 4; ++e) { v0[e] = gelu_tanh_f(v0[e]); v1[e] = gelu_tanh_f(v1[e]); }
;                                 dst = O3 + row * 256 + cl;
;                             } else {
; #pragma unroll
;                                 for (int e = 0; e < 4; ++e) { v0[e] = fmaxf(sigmoid_f(v0[e]), 1e-13f); v1[e] = fmaxf(sigmoid_f(v1[e]), 1e-13f); }
;                                 dst = O4 + row * 3072 + (pn - 6) * 256 + cl;
;                             }
;                             u32x4 w; w.x = pk2(v0[0], v0[1]); w.y = pk2(v0[2], v0[3]); w.z = pk2(v1[0], v1[1]); w.w = pk2(v1[2], v1[3]);
;                             if (pn >= 6) __builtin_nontemporal_store(w, (u32x4*)dst); else *(u32x4*)dst = w;
;                         }
.LBB0_553:
	s_and_b64 vcc, exec, s[30:31]
	s_cbranch_vccz .LBB0_539
	v_cvt_pk_bf16_f32 v148, v12, v13
	v_cvt_pk_bf16_f32 v149, v14, v15
	v_cvt_pk_bf16_f32 v150, v8, v9
	v_cvt_pk_bf16_f32 v151, v10, v11
	v_lshl_add_u64 v[134:135], v[140:141], 0, v[128:129]
	global_store_dwordx4 v[134:135], v[148:151], off sc0 sc1
	s_and_b64 vcc, exec, s[6:7]
	s_mov_b64 s[6:7], -1
	s_cbranch_vccz .LBB0_540
.LBB0_555:
	s_and_b64 vcc, exec, s[6:7]
	s_cbranch_vccz .LBB0_557
	v_cvt_pk_bf16_f32 v130, v4, v5
	v_cvt_pk_bf16_f32 v131, v6, v7
	v_cvt_pk_bf16_f32 v132, v0, v1
	v_cvt_pk_bf16_f32 v133, v2, v3
	v_lshl_add_u64 v[128:129], v[142:143], 0, v[128:129]
	global_store_dwordx4 v[128:129], v[130:133], off sc0 sc1
